# P7 fast path: skip the max tree / rescale factor on tiles that provably cannot raise any running maximum (Cauchy-Schwarz bound), exact
# speedup vs baseline: 1.0260x; 1.0010x over previous
.Lsp_par_done:
	v_readfirstlane_b32 s21, v5
	s_ashr_i32 s20, s21, 6
	s_add_i32 s80, s25, -1
	v_bfe_u32 v0, v5, 4, 2
	s_and_b32 s22, s20, 3
	s_lshl_b32 s26, s20, 3
	s_ashr_i32 s81, s80, 31
	v_or_b32_e32 v4, s26, v0
	v_lshlrev_b32_e32 v6, 5, v0
	v_bitop3_b32 v0, s26, v5, v0 bitop3:0x36
	s_lshl_b32 s30, s22, 5
	s_max_i32 s31, s25, 2
	s_lshl_b64 s[26:27], s[80:81], 16
	v_and_b32_e32 v3, 15, v5
	v_lshlrev_b32_e32 v8, 9, v4
	v_lshlrev_b32_e32 v0, 3, v0
	s_add_u32 s28, s48, s26
	v_lshlrev_b32_e32 v7, 3, v3
	v_and_or_b32 v0, v0, s11, v8
	s_addc_u32 s29, s49, s27
	v_lshlrev_b32_e32 v188, 1, v0
	v_bitop3_b32 v0, v8, v6, v7 bitop3:0xf6
	s_add_u32 s34, s60, s26
	v_lshlrev_b32_e32 v190, 1, v0
	v_or_b32_e32 v0, 4, v4
	v_bitop3_b32 v4, v4, v5, 4 bitop3:0x36
	s_addc_u32 s35, s61, s27
	s_lshl_b32 s26, s20, 11
	v_lshlrev_b32_e32 v0, 9, v0
	v_lshlrev_b32_e32 v4, 3, v4
	s_add_i32 s26, s26, 0
	v_mov_b32_e32 v189, v1
	v_and_or_b32 v4, v4, s11, v0
	s_add_i32 s27, s26, 0x4000
	v_lshl_add_u64 v[8:9], s[28:29], 0, v[188:189]
	s_mov_b32 m0, s26
	s_nop 0
	global_load_lds_dwordx4 v[8:9], off
	v_mov_b32_e32 v191, v1
	v_lshlrev_b32_e32 v192, 1, v4
	v_bitop3_b32 v0, v0, v6, v7 bitop3:0xf6
	v_lshl_add_u64 v[8:9], s[34:35], 0, v[190:191]
	s_mov_b32 m0, s27
	s_nop 0
	global_load_lds_dwordx4 v[8:9], off
	v_mov_b32_e32 v193, v1
	s_add_i32 s27, s26, 0x400
	s_add_i32 s72, s31, -2
	v_lshlrev_b32_e32 v194, 1, v0
	v_lshl_add_u64 v[8:9], s[28:29], 0, v[192:193]
	s_mov_b32 m0, s27
	s_nop 0
	global_load_lds_dwordx4 v[8:9], off
	v_mov_b32_e32 v195, v1
	s_add_i32 s27, s26, 0x4400
	s_ashr_i32 s46, s21, 8
	s_lshl_b64 s[28:29], s[72:73], 16
	v_lshl_add_u64 v[8:9], s[34:35], 0, v[194:195]
	s_add_u32 s34, s48, s28
	s_addc_u32 s35, s49, s29
	s_add_u32 s28, s60, s28
	s_mov_b32 m0, s27
	s_nop 0
	global_load_lds_dwordx4 v[8:9], off
	s_addc_u32 s29, s61, s29
	v_lshl_add_u64 v[8:9], s[34:35], 0, v[188:189]
	v_and_b32_e32 v2, 31, v5
	s_add_i32 s27, s26, 0x8000
	s_mov_b32 m0, s27
	s_nop 0
	global_load_lds_dwordx4 v[8:9], off
	v_lshl_add_u64 v[8:9], s[28:29], 0, v[190:191]
	s_add_i32 s31, s26, 0xc000
	s_mov_b32 m0, s31
	s_nop 0
	global_load_lds_dwordx4 v[8:9], off
	v_lshl_add_u64 v[8:9], s[34:35], 0, v[192:193]
	v_or_b32_e32 v226, s30, v2
	s_add_i32 s27, s26, 0x8400
	s_mov_b32 m0, s27
	s_nop 0
	global_load_lds_dwordx4 v[8:9], off
	v_lshl_add_u64 v[8:9], s[28:29], 0, v[194:195]
	v_lshlrev_b32_e32 v0, 11, v226
	s_lshl_b32 s28, s46, 6
	v_bfe_u32 v4, v5, 5, 1
	s_add_i32 s27, s26, 0xc400
	s_mov_b32 m0, s27
	s_nop 0
	global_load_lds_dwordx4 v[8:9], off
	v_lshl_add_u64 v[8:9], s[38:39], 0, v[0:1]
	s_ashr_i32 s29, s28, 31
	v_lshl_add_u64 v[8:9], s[28:29], 1, v[8:9]
	v_lshlrev_b32_e32 v0, 4, v4
	v_lshl_add_u64 v[8:9], v[8:9], 0, v[0:1]
	global_load_dwordx4 v[144:147], v[8:9], off
	global_load_dwordx4 v[148:151], v[8:9], off offset:32
	global_load_dwordx4 v[152:155], v[8:9], off offset:64
	global_load_dwordx4 v[156:159], v[8:9], off offset:96
	v_readlane_b32 s12, v253, 34
	s_waitcnt vmcnt(0)
	v_readlane_b32 s13, v253, 35
	v_and_b32_e32 v203, 63, v5
	s_or_b64 s[82:83], s[0:1], s[12:13]
	v_mov_b32_e32 v231, 0x7f61b1e6
	s_and_b64 vcc, exec, s[82:83]
	v_cmp_eq_u32_e64 s[0:1], 0, v203
	s_waitcnt vmcnt(3)
	s_waitcnt vmcnt(2)
	s_waitcnt vmcnt(1)
	s_waitcnt vmcnt(0)
	s_lshl_b32 s72, s36, 1
	s_lshl_b64 s[28:29], s[72:73], 2
	v_readlane_b32 s12, v253, 25
	v_readlane_b32 s13, v253, 26
	s_add_u32 s27, s12, s28
	s_addc_u32 s31, s13, s29
	v_and_b32_e32 v7, 0xffff0000, v144
	s_ashr_i32 s47, s46, 31
	v_lshlrev_b32_e32 v0, 16, v144
	v_mul_f32_e32 v7, v7, v7
	s_lshl_b64 s[28:29], s[46:47], 2
	v_fmac_f32_e32 v7, v0, v0
	v_lshlrev_b32_e32 v0, 16, v145
	s_add_u32 s28, s27, s28
	v_fmac_f32_e32 v7, v0, v0
	v_and_b32_e32 v0, 0xffff0000, v145
	s_addc_u32 s29, s31, s29
	v_fmac_f32_e32 v7, v0, v0
	global_load_dword v0, v1, s[28:29]
	v_lshlrev_b32_e32 v8, 16, v146
	v_fmac_f32_e32 v7, v8, v8
	v_and_b32_e32 v8, 0xffff0000, v146
	v_fmac_f32_e32 v7, v8, v8
	v_lshlrev_b32_e32 v8, 16, v147
	v_fmac_f32_e32 v7, v8, v8
	v_and_b32_e32 v8, 0xffff0000, v147
	v_fmac_f32_e32 v7, v8, v8
	v_lshlrev_b32_e32 v8, 16, v148
	v_fmac_f32_e32 v7, v8, v8
	v_and_b32_e32 v8, 0xffff0000, v148
	v_fmac_f32_e32 v7, v8, v8
	v_lshlrev_b32_e32 v8, 16, v149
	v_fmac_f32_e32 v7, v8, v8
	v_and_b32_e32 v8, 0xffff0000, v149
	v_fmac_f32_e32 v7, v8, v8
	v_lshlrev_b32_e32 v8, 16, v150
	v_fmac_f32_e32 v7, v8, v8
	v_and_b32_e32 v8, 0xffff0000, v150
	v_fmac_f32_e32 v7, v8, v8
	v_lshlrev_b32_e32 v8, 16, v151
	v_fmac_f32_e32 v7, v8, v8
	v_and_b32_e32 v8, 0xffff0000, v151
	v_fmac_f32_e32 v7, v8, v8
	v_lshlrev_b32_e32 v8, 16, v152
	v_fmac_f32_e32 v7, v8, v8
	v_and_b32_e32 v8, 0xffff0000, v152
	v_fmac_f32_e32 v7, v8, v8
	v_lshlrev_b32_e32 v8, 16, v153
	v_fmac_f32_e32 v7, v8, v8
	v_and_b32_e32 v8, 0xffff0000, v153
	v_fmac_f32_e32 v7, v8, v8
	v_lshlrev_b32_e32 v8, 16, v154
	v_fmac_f32_e32 v7, v8, v8
	v_and_b32_e32 v8, 0xffff0000, v154
	v_fmac_f32_e32 v7, v8, v8
	v_lshlrev_b32_e32 v8, 16, v155
	v_fmac_f32_e32 v7, v8, v8
	v_and_b32_e32 v8, 0xffff0000, v155
	v_fmac_f32_e32 v7, v8, v8
	v_and_b32_e32 v9, 0xffff0000, v156
	v_lshlrev_b32_e32 v8, 16, v156
	v_pk_mul_f32 v[8:9], v[8:9], v[8:9]
	s_mov_b32 s12, 0xf800000
	v_add_f32_e32 v7, v8, v7
	v_add_f32_e32 v7, v9, v7
	v_and_b32_e32 v9, 0xffff0000, v157
	v_lshlrev_b32_e32 v8, 16, v157
	v_pk_mul_f32 v[8:9], v[8:9], v[8:9]
	s_nop 0
	v_add_f32_e32 v7, v8, v7
	v_add_f32_e32 v7, v9, v7
	v_and_b32_e32 v9, 0xffff0000, v158
	v_lshlrev_b32_e32 v8, 16, v158
	v_pk_mul_f32 v[8:9], v[8:9], v[8:9]
	s_nop 0
	v_add_f32_e32 v7, v8, v7
	v_add_f32_e32 v7, v9, v7
	v_and_b32_e32 v9, 0xffff0000, v159
	v_lshlrev_b32_e32 v8, 16, v159
	v_pk_mul_f32 v[8:9], v[8:9], v[8:9]
	s_nop 0
	v_add_f32_e32 v7, v8, v7
	v_add_f32_e32 v7, v9, v7
	ds_bpermute_b32 v8, v225, v7
	s_waitcnt lgkmcnt(0)
	v_add_f32_e32 v7, v7, v8
	v_mul_f32_e32 v8, 0x4f800000, v7
	v_cmp_gt_f32_e32 vcc, s12, v7
	s_nop 1
	v_cndmask_b32_e32 v7, v7, v8, vcc
	v_sqrt_f32_e32 v8, v7
	s_nop 0
	v_add_u32_e32 v9, -1, v8
	v_fma_f32 v10, -v9, v8, v7
	v_cmp_ge_f32_e64 s[38:39], 0, v10
	v_add_u32_e32 v10, 1, v8
	v_fma_f32 v11, -v10, v8, v7
	v_cmp_lt_f32_e64 s[42:43], 0, v11
	s_and_saveexec_b64 s[84:85], s[0:1]
	s_cbranch_execz .LBB0_454
	s_lshl_b32 s0, s20, 2
	s_add_i32 s0, s0, 0
	s_add_i32 s0, s0, 0x20040
	v_mov_b32_e32 v11, s0
	ds_write_b32 v11, v1
	ds_write_b32 v11, v1 offset:32

.Lfa_body:
	s_add_i32 s25, s25, -1
	v_add_u32_e32 v0, s30, v233
	v_add_u32_e32 v14, s30, v234
	v_add_u32_e32 v15, s30, v235
	v_add_u32_e32 v238, s30, v236
	ds_read_b128 v[2:5], v0
	ds_read_b128 v[6:9], v0 offset:8192
	ds_read_b128 v[10:13], v14
	ds_read_b128 v[212:215], v14 offset:8192
	ds_read_b128 v[240:243], v15
	ds_read_b128 v[244:247], v15 offset:8192
	v_add_u32_e32 v248, s27, v227
	v_add_u32_e32 v249, s27, v228
	v_add_u32_e32 v250, s27, v229
	v_add_u32_e32 v251, s27, v230
	s_waitcnt lgkmcnt(4)
	v_mfma_f32_32x32x16_bf16 v[128:143], v[2:5], v[144:147], v[80:95]
	v_mfma_f32_32x32x16_bf16 v[112:127], v[6:9], v[144:147], v[96:111]
	ds_read_b128 v[2:5], v238
	ds_read_b128 v[6:9], v238 offset:8192
	s_waitcnt lgkmcnt(4)
	v_mfma_f32_32x32x16_bf16 v[128:143], v[10:13], v[148:151], v[128:143]
	v_mfma_f32_32x32x16_bf16 v[112:127], v[212:215], v[148:151], v[112:127]
	ds_read_b64_tr_b16 v[10:11], v248 offset:0
	ds_read_b64_tr_b16 v[12:13], v248 offset:2048
	ds_read_b64_tr_b16 v[212:213], v249 offset:0
	ds_read_b64_tr_b16 v[214:215], v249 offset:2048
	s_waitcnt lgkmcnt(6)
	v_mfma_f32_32x32x16_bf16 v[128:143], v[240:243], v[152:155], v[128:143]
	v_mfma_f32_32x32x16_bf16 v[112:127], v[244:247], v[152:155], v[112:127]
	ds_read_b64_tr_b16 v[240:241], v250 offset:0
	ds_read_b64_tr_b16 v[242:243], v250 offset:2048
	ds_read_b64_tr_b16 v[244:245], v251 offset:0
	ds_read_b64_tr_b16 v[246:247], v251 offset:2048
	s_waitcnt lgkmcnt(8)
	v_mfma_f32_32x32x16_bf16 v[128:143], v[2:5], v[156:159], v[128:143]
	v_mfma_f32_32x32x16_bf16 v[112:127], v[6:9], v[156:159], v[112:127]
	ds_read_b64_tr_b16 v[2:3], v248 offset:4096
	ds_read_b64_tr_b16 v[4:5], v248 offset:6144
	ds_read_b64_tr_b16 v[6:7], v249 offset:4096
	ds_read_b64_tr_b16 v[8:9], v249 offset:6144
	s_add_i32 s19, s67, 63
	v_subrev_u32_e32 v14, s19, v198
	v_cvt_f32_i32_e32 v14, v14
	v_cvt_f32_u32_e32 v15, s67
	v_fma_f32 v14, -v196, v14, v231
	v_mul_f32_e32 v200, v196, v15
	v_cmp_lt_f32_e32 vcc, v14, v201
	s_cmp_eq_u64 vcc, exec
	s_cbranch_scc1 .Lfa_nomax
	s_waitcnt lgkmcnt(10)
	v_mfma_f32_32x32x16_bf16 v[64:79], v[10:13], v[172:175], v[64:79]
	ds_read_b64_tr_b16 v[10:11], v250 offset:4096
	ds_read_b64_tr_b16 v[12:13], v250 offset:6144
	s_waitcnt lgkmcnt(10)
	v_mfma_f32_32x32x16_bf16 v[48:63], v[212:215], v[172:175], v[48:63]
	ds_read_b64_tr_b16 v[212:213], v251 offset:4096
	ds_read_b64_tr_b16 v[214:215], v251 offset:6144
	v_max3_f32 v0, v128, s14, v129
	v_max3_f32 v0, v0, v130, v131
	v_max3_f32 v0, v0, v132, v133
	v_max3_f32 v0, v0, v134, v135
	s_waitcnt lgkmcnt(10)
	v_mfma_f32_32x32x16_bf16 v[32:47], v[240:243], v[172:175], v[32:47]
	ds_read_b64_tr_b16 v[240:241], v248 offset:8192
	ds_read_b64_tr_b16 v[242:243], v248 offset:10240
	v_max3_f32 v0, v0, v136, v137
	v_max3_f32 v0, v0, v138, v139
	v_max3_f32 v0, v0, v140, v141
	v_max3_f32 v0, v0, v142, v143
	s_waitcnt lgkmcnt(10)
	v_mfma_f32_32x32x16_bf16 v[16:31], v[244:247], v[172:175], v[16:31]
	ds_read_b64_tr_b16 v[244:245], v249 offset:8192
	ds_read_b64_tr_b16 v[246:247], v249 offset:10240
	v_max3_f32 v0, v0, v112, v113
	v_max3_f32 v0, v0, v114, v115
	v_max3_f32 v0, v0, v116, v117
	v_max3_f32 v0, v0, v118, v119
	v_max3_f32 v0, v0, v120, v121
	v_max3_f32 v0, v0, v122, v123
	v_max3_f32 v0, v0, v124, v125
	v_max3_f32 v0, v0, v126, v127
	ds_bpermute_b32 v15, v225, v0
	v_max_f32_e32 v0, v0, v0
	s_waitcnt lgkmcnt(11)
	v_mfma_f32_32x32x16_bf16 v[64:79], v[2:5], v[168:171], v[64:79]
	ds_read_b64_tr_b16 v[2:3], v250 offset:8192
	ds_read_b64_tr_b16 v[4:5], v250 offset:10240
	s_waitcnt lgkmcnt(11)
	v_mfma_f32_32x32x16_bf16 v[48:63], v[6:9], v[168:171], v[48:63]
	ds_read_b64_tr_b16 v[6:7], v251 offset:8192
	ds_read_b64_tr_b16 v[8:9], v251 offset:10240
	s_waitcnt lgkmcnt(4)
	v_max_f32_e32 v15, v15, v15
	v_max_f32_e32 v176, v0, v15
	v_add_f32_e32 v14, v200, v176
	v_max_f32_e32 v0, v14, v14
	v_max_f32_e32 v14, v201, v201
	v_max_f32_e32 v14, v14, v0
	v_mfma_f32_32x32x16_bf16 v[32:47], v[10:13], v[168:171], v[32:47]
	ds_read_b64_tr_b16 v[10:11], v248 offset:12288
	ds_read_b64_tr_b16 v[12:13], v248 offset:14336
	v_sub_f32_e32 v0, v201, v14
	v_exp_f32_e32 v0, v0
	v_sub_f32_e32 v15, v200, v14
	v_cmp_eq_f32_e32 vcc, 1.0, v0
	s_cmp_eq_u64 vcc, exec
	s_cselect_b64 s[42:43], 0, -1
	v_mov_b32_e32 v201, v14
	v_add_f32_e32 v128, v128, v15
	v_exp_f32_e32 v128, v128
	v_add_f32_e32 v129, v129, v15
	v_exp_f32_e32 v129, v129
	v_add_f32_e32 v238, 0, v128
	v_add_f32_e32 v130, v130, v15
	v_exp_f32_e32 v130, v130
	v_add_f32_e32 v238, v129, v238
	v_mfma_f32_32x32x16_bf16 v[16:31], v[212:215], v[168:171], v[16:31]
	ds_read_b64_tr_b16 v[212:213], v249 offset:12288
	ds_read_b64_tr_b16 v[214:215], v249 offset:14336
	v_add_f32_e32 v131, v131, v15
	v_exp_f32_e32 v131, v131
	v_add_f32_e32 v238, v130, v238
	v_add_f32_e32 v132, v132, v15
	v_exp_f32_e32 v132, v132
	v_add_f32_e32 v238, v131, v238
	v_add_f32_e32 v133, v133, v15
	v_exp_f32_e32 v133, v133
	v_add_f32_e32 v238, v132, v238
	v_add_f32_e32 v134, v134, v15
	v_exp_f32_e32 v134, v134
	v_add_f32_e32 v238, v133, v238
	v_mfma_f32_32x32x16_bf16 v[64:79], v[240:243], v[164:167], v[64:79]
	ds_read_b64_tr_b16 v[240:241], v250 offset:12288
	ds_read_b64_tr_b16 v[242:243], v250 offset:14336
	v_add_f32_e32 v135, v135, v15
	v_exp_f32_e32 v135, v135
	v_add_f32_e32 v238, v134, v238
	v_cvt_pk_bf16_f32 v172, v128, v129
	v_cvt_pk_bf16_f32 v173, v130, v131
	v_cvt_pk_bf16_f32 v174, v132, v133
	v_cvt_pk_bf16_f32 v175, v134, v135
	v_add_f32_e32 v136, v136, v15
	v_exp_f32_e32 v136, v136
	v_add_f32_e32 v238, v135, v238
	v_add_f32_e32 v137, v137, v15
	v_exp_f32_e32 v137, v137
	v_add_f32_e32 v238, v136, v238
	v_mfma_f32_32x32x16_bf16 v[48:63], v[244:247], v[164:167], v[48:63]
	ds_read_b64_tr_b16 v[244:245], v251 offset:12288
	ds_read_b64_tr_b16 v[246:247], v251 offset:14336
	v_add_f32_e32 v138, v138, v15
	v_exp_f32_e32 v138, v138
	v_add_f32_e32 v238, v137, v238
	v_add_f32_e32 v139, v139, v15
	v_exp_f32_e32 v139, v139
	v_add_f32_e32 v238, v138, v238
	v_add_f32_e32 v140, v140, v15
	v_exp_f32_e32 v140, v140
	v_add_f32_e32 v238, v139, v238
	v_add_f32_e32 v141, v141, v15
	v_exp_f32_e32 v141, v141
	v_add_f32_e32 v238, v140, v238
	s_waitcnt lgkmcnt(10)
	v_mfma_f32_32x32x16_bf16 v[32:47], v[2:5], v[164:167], v[32:47]
	v_add_f32_e32 v142, v142, v15
	v_exp_f32_e32 v142, v142
	v_add_f32_e32 v238, v141, v238
	v_add_f32_e32 v143, v143, v15
	v_exp_f32_e32 v143, v143
	v_add_f32_e32 v238, v142, v238
	v_cvt_pk_bf16_f32 v168, v136, v137
	v_cvt_pk_bf16_f32 v169, v138, v139
	v_cvt_pk_bf16_f32 v170, v140, v141
	v_cvt_pk_bf16_f32 v171, v142, v143
	v_add_f32_e32 v112, v112, v15
	v_exp_f32_e32 v112, v112
	v_add_f32_e32 v238, v143, v238
	v_add_f32_e32 v113, v113, v15
	v_exp_f32_e32 v113, v113
	v_add_f32_e32 v238, v112, v238
	s_waitcnt lgkmcnt(8)
	v_mfma_f32_32x32x16_bf16 v[16:31], v[6:9], v[164:167], v[16:31]
	v_add_f32_e32 v114, v114, v15
	v_exp_f32_e32 v114, v114
	v_add_f32_e32 v238, v113, v238
	v_add_f32_e32 v115, v115, v15
	v_exp_f32_e32 v115, v115
	v_add_f32_e32 v238, v114, v238
	v_add_f32_e32 v116, v116, v15
	v_exp_f32_e32 v116, v116
	v_add_f32_e32 v238, v115, v238
	v_add_f32_e32 v117, v117, v15
	v_exp_f32_e32 v117, v117
	v_add_f32_e32 v238, v116, v238
	s_waitcnt lgkmcnt(6)
	v_mfma_f32_32x32x16_bf16 v[64:79], v[10:13], v[160:163], v[64:79]
	v_add_f32_e32 v118, v118, v15
	v_exp_f32_e32 v118, v118
	v_add_f32_e32 v238, v117, v238
	v_add_f32_e32 v119, v119, v15
	v_exp_f32_e32 v119, v119
	v_add_f32_e32 v238, v118, v238
	v_cvt_pk_bf16_f32 v164, v112, v113
	v_cvt_pk_bf16_f32 v165, v114, v115
	v_cvt_pk_bf16_f32 v166, v116, v117
	v_cvt_pk_bf16_f32 v167, v118, v119
	v_add_f32_e32 v120, v120, v15
	v_exp_f32_e32 v120, v120
	v_add_f32_e32 v238, v119, v238
	s_waitcnt lgkmcnt(4)
	v_mfma_f32_32x32x16_bf16 v[48:63], v[212:215], v[160:163], v[48:63]
	v_add_f32_e32 v121, v121, v15
	v_exp_f32_e32 v121, v121
	v_add_f32_e32 v238, v120, v238
	v_add_f32_e32 v122, v122, v15
	v_exp_f32_e32 v122, v122
	v_add_f32_e32 v238, v121, v238
	s_waitcnt lgkmcnt(2)
	v_mfma_f32_32x32x16_bf16 v[32:47], v[240:243], v[160:163], v[32:47]
	v_add_f32_e32 v123, v123, v15
	v_exp_f32_e32 v123, v123
	v_add_f32_e32 v238, v122, v238
	v_add_f32_e32 v124, v124, v15
	v_exp_f32_e32 v124, v124
	v_add_f32_e32 v238, v123, v238
	s_waitcnt lgkmcnt(0)
	v_mfma_f32_32x32x16_bf16 v[16:31], v[244:247], v[160:163], v[16:31]
	v_add_f32_e32 v125, v125, v15
	v_exp_f32_e32 v125, v125
	v_add_f32_e32 v238, v124, v238
	v_add_f32_e32 v126, v126, v15
	v_exp_f32_e32 v126, v126
	v_add_f32_e32 v238, v125, v238
	v_add_f32_e32 v127, v127, v15
	v_exp_f32_e32 v127, v127
	v_add_f32_e32 v238, v126, v238
	v_cvt_pk_bf16_f32 v160, v120, v121
	v_cvt_pk_bf16_f32 v161, v122, v123
	v_cvt_pk_bf16_f32 v162, v124, v125
	v_cvt_pk_bf16_f32 v163, v126, v127
	v_add_f32_e32 v238, v127, v238
	v_fmac_f32_e32 v238, v232, v0
	s_mov_b32 s27, s30
	v_mov_b32_e32 v232, v238
	s_and_b64 vcc, exec, s[42:43]
	s_cbranch_vccz .Lfa_noresc
	s_nop 15
	v_pk_mul_f32 v[78:79], v[78:79], v[0:1] op_sel_hi:[1,0]
	v_pk_mul_f32 v[76:77], v[76:77], v[0:1] op_sel_hi:[1,0]
	v_pk_mul_f32 v[74:75], v[74:75], v[0:1] op_sel_hi:[1,0]
	v_pk_mul_f32 v[72:73], v[72:73], v[0:1] op_sel_hi:[1,0]
	v_pk_mul_f32 v[70:71], v[70:71], v[0:1] op_sel_hi:[1,0]
	v_pk_mul_f32 v[68:69], v[68:69], v[0:1] op_sel_hi:[1,0]
	v_pk_mul_f32 v[66:67], v[66:67], v[0:1] op_sel_hi:[1,0]
	v_pk_mul_f32 v[64:65], v[64:65], v[0:1] op_sel_hi:[1,0]
	v_pk_mul_f32 v[62:63], v[62:63], v[0:1] op_sel_hi:[1,0]
	v_pk_mul_f32 v[60:61], v[60:61], v[0:1] op_sel_hi:[1,0]
	v_pk_mul_f32 v[58:59], v[58:59], v[0:1] op_sel_hi:[1,0]
	v_pk_mul_f32 v[56:57], v[56:57], v[0:1] op_sel_hi:[1,0]
	v_pk_mul_f32 v[54:55], v[54:55], v[0:1] op_sel_hi:[1,0]
	v_pk_mul_f32 v[52:53], v[52:53], v[0:1] op_sel_hi:[1,0]
	v_pk_mul_f32 v[50:51], v[50:51], v[0:1] op_sel_hi:[1,0]
	v_pk_mul_f32 v[48:49], v[48:49], v[0:1] op_sel_hi:[1,0]
	v_pk_mul_f32 v[46:47], v[46:47], v[0:1] op_sel_hi:[1,0]
	v_pk_mul_f32 v[44:45], v[44:45], v[0:1] op_sel_hi:[1,0]
	v_pk_mul_f32 v[42:43], v[42:43], v[0:1] op_sel_hi:[1,0]
	v_pk_mul_f32 v[40:41], v[40:41], v[0:1] op_sel_hi:[1,0]
	v_pk_mul_f32 v[38:39], v[38:39], v[0:1] op_sel_hi:[1,0]
	v_pk_mul_f32 v[36:37], v[36:37], v[0:1] op_sel_hi:[1,0]
	v_pk_mul_f32 v[34:35], v[34:35], v[0:1] op_sel_hi:[1,0]
	v_pk_mul_f32 v[32:33], v[32:33], v[0:1] op_sel_hi:[1,0]
	v_pk_mul_f32 v[30:31], v[30:31], v[0:1] op_sel_hi:[1,0]
	v_pk_mul_f32 v[28:29], v[28:29], v[0:1] op_sel_hi:[1,0]
	v_pk_mul_f32 v[26:27], v[26:27], v[0:1] op_sel_hi:[1,0]
	v_pk_mul_f32 v[24:25], v[24:25], v[0:1] op_sel_hi:[1,0]
	v_pk_mul_f32 v[22:23], v[22:23], v[0:1] op_sel_hi:[1,0]
	v_pk_mul_f32 v[20:21], v[20:21], v[0:1] op_sel_hi:[1,0]
	v_pk_mul_f32 v[18:19], v[18:19], v[0:1] op_sel_hi:[1,0]
	v_pk_mul_f32 v[16:17], v[16:17], v[0:1] op_sel_hi:[1,0]

.Lfa_nomax:
	s_waitcnt lgkmcnt(10)
	v_mfma_f32_32x32x16_bf16 v[64:79], v[10:13], v[172:175], v[64:79]
	ds_read_b64_tr_b16 v[10:11], v250 offset:4096
	ds_read_b64_tr_b16 v[12:13], v250 offset:6144
	s_waitcnt lgkmcnt(10)
	v_mfma_f32_32x32x16_bf16 v[48:63], v[212:215], v[172:175], v[48:63]
	ds_read_b64_tr_b16 v[212:213], v251 offset:4096
	ds_read_b64_tr_b16 v[214:215], v251 offset:6144
	v_mov_b32_e32 v0, 1.0
	v_sub_f32_e32 v15, v200, v201
	v_add_f32_e32 v128, v128, v15
	v_exp_f32_e32 v128, v128
	v_add_f32_e32 v129, v129, v15
	v_exp_f32_e32 v129, v129
	v_add_f32_e32 v238, 0, v128
	s_waitcnt lgkmcnt(10)
	v_mfma_f32_32x32x16_bf16 v[32:47], v[240:243], v[172:175], v[32:47]
	ds_read_b64_tr_b16 v[240:241], v248 offset:8192
	ds_read_b64_tr_b16 v[242:243], v248 offset:10240
	v_add_f32_e32 v130, v130, v15
	v_exp_f32_e32 v130, v130
	v_add_f32_e32 v238, v129, v238
	v_add_f32_e32 v131, v131, v15
	v_exp_f32_e32 v131, v131
	v_add_f32_e32 v238, v130, v238
	s_waitcnt lgkmcnt(10)
	v_mfma_f32_32x32x16_bf16 v[16:31], v[244:247], v[172:175], v[16:31]
	ds_read_b64_tr_b16 v[244:245], v249 offset:8192
	ds_read_b64_tr_b16 v[246:247], v249 offset:10240
	v_add_f32_e32 v132, v132, v15
	v_exp_f32_e32 v132, v132
	v_add_f32_e32 v238, v131, v238
	v_add_f32_e32 v133, v133, v15
	v_exp_f32_e32 v133, v133
	v_add_f32_e32 v238, v132, v238
	v_add_f32_e32 v134, v134, v15
	v_exp_f32_e32 v134, v134
	v_add_f32_e32 v238, v133, v238
	s_waitcnt lgkmcnt(10)
	v_mfma_f32_32x32x16_bf16 v[64:79], v[2:5], v[168:171], v[64:79]
	ds_read_b64_tr_b16 v[2:3], v250 offset:8192
	ds_read_b64_tr_b16 v[4:5], v250 offset:10240
	v_add_f32_e32 v135, v135, v15
	v_exp_f32_e32 v135, v135
	v_add_f32_e32 v238, v134, v238
	v_cvt_pk_bf16_f32 v172, v128, v129
	v_cvt_pk_bf16_f32 v173, v130, v131
	v_cvt_pk_bf16_f32 v174, v132, v133
	v_cvt_pk_bf16_f32 v175, v134, v135
	v_add_f32_e32 v136, v136, v15
	v_exp_f32_e32 v136, v136
	v_add_f32_e32 v238, v135, v238
	s_waitcnt lgkmcnt(10)
	v_mfma_f32_32x32x16_bf16 v[48:63], v[6:9], v[168:171], v[48:63]
	ds_read_b64_tr_b16 v[6:7], v251 offset:8192
	ds_read_b64_tr_b16 v[8:9], v251 offset:10240
	v_add_f32_e32 v137, v137, v15
	v_exp_f32_e32 v137, v137
	v_add_f32_e32 v238, v136, v238
	v_add_f32_e32 v138, v138, v15
	v_exp_f32_e32 v138, v138
	v_add_f32_e32 v238, v137, v238
	v_add_f32_e32 v139, v139, v15
	v_exp_f32_e32 v139, v139
	v_add_f32_e32 v238, v138, v238
	s_waitcnt lgkmcnt(10)
	v_mfma_f32_32x32x16_bf16 v[32:47], v[10:13], v[168:171], v[32:47]
	ds_read_b64_tr_b16 v[10:11], v248 offset:12288
	ds_read_b64_tr_b16 v[12:13], v248 offset:14336
	v_add_f32_e32 v140, v140, v15
	v_exp_f32_e32 v140, v140
	v_add_f32_e32 v238, v139, v238
	v_add_f32_e32 v141, v141, v15
	v_exp_f32_e32 v141, v141
	v_add_f32_e32 v238, v140, v238
	s_waitcnt lgkmcnt(10)
	v_mfma_f32_32x32x16_bf16 v[16:31], v[212:215], v[168:171], v[16:31]
	ds_read_b64_tr_b16 v[212:213], v249 offset:12288
	ds_read_b64_tr_b16 v[214:215], v249 offset:14336
	v_add_f32_e32 v142, v142, v15
	v_exp_f32_e32 v142, v142
	v_add_f32_e32 v238, v141, v238
	v_add_f32_e32 v143, v143, v15
	v_exp_f32_e32 v143, v143
	v_add_f32_e32 v238, v142, v238
	v_cvt_pk_bf16_f32 v168, v136, v137
	v_cvt_pk_bf16_f32 v169, v138, v139
	v_cvt_pk_bf16_f32 v170, v140, v141
	v_cvt_pk_bf16_f32 v171, v142, v143
	v_add_f32_e32 v112, v112, v15
	v_exp_f32_e32 v112, v112
	v_add_f32_e32 v238, v143, v238
	s_waitcnt lgkmcnt(10)
	v_mfma_f32_32x32x16_bf16 v[64:79], v[240:243], v[164:167], v[64:79]
	ds_read_b64_tr_b16 v[240:241], v250 offset:12288
	ds_read_b64_tr_b16 v[242:243], v250 offset:14336
	v_add_f32_e32 v113, v113, v15
	v_exp_f32_e32 v113, v113
	v_add_f32_e32 v238, v112, v238
	v_add_f32_e32 v114, v114, v15
	v_exp_f32_e32 v114, v114
	v_add_f32_e32 v238, v113, v238
	s_waitcnt lgkmcnt(10)
	v_mfma_f32_32x32x16_bf16 v[48:63], v[244:247], v[164:167], v[48:63]
	ds_read_b64_tr_b16 v[244:245], v251 offset:12288
	ds_read_b64_tr_b16 v[246:247], v251 offset:14336
	v_add_f32_e32 v115, v115, v15
	v_exp_f32_e32 v115, v115
	v_add_f32_e32 v238, v114, v238
	v_add_f32_e32 v116, v116, v15
	v_exp_f32_e32 v116, v116
	v_add_f32_e32 v238, v115, v238
	v_add_f32_e32 v117, v117, v15
	v_exp_f32_e32 v117, v117
	v_add_f32_e32 v238, v116, v238
	s_waitcnt lgkmcnt(10)
	v_mfma_f32_32x32x16_bf16 v[32:47], v[2:5], v[164:167], v[32:47]
	v_add_f32_e32 v118, v118, v15
	v_exp_f32_e32 v118, v118
	v_add_f32_e32 v238, v117, v238
	s_waitcnt lgkmcnt(8)
	v_mfma_f32_32x32x16_bf16 v[16:31], v[6:9], v[164:167], v[16:31]
	v_add_f32_e32 v119, v119, v15
	v_exp_f32_e32 v119, v119
	v_add_f32_e32 v238, v118, v238
	v_cvt_pk_bf16_f32 v164, v112, v113
	v_cvt_pk_bf16_f32 v165, v114, v115
	v_cvt_pk_bf16_f32 v166, v116, v117
	v_cvt_pk_bf16_f32 v167, v118, v119
	v_add_f32_e32 v120, v120, v15
	v_exp_f32_e32 v120, v120
	v_add_f32_e32 v238, v119, v238
	s_waitcnt lgkmcnt(6)
	v_mfma_f32_32x32x16_bf16 v[64:79], v[10:13], v[160:163], v[64:79]
	v_add_f32_e32 v121, v121, v15
	v_exp_f32_e32 v121, v121
	v_add_f32_e32 v238, v120, v238
	v_add_f32_e32 v122, v122, v15
	v_exp_f32_e32 v122, v122
	v_add_f32_e32 v238, v121, v238
	s_waitcnt lgkmcnt(4)
	v_mfma_f32_32x32x16_bf16 v[48:63], v[212:215], v[160:163], v[48:63]
	v_add_f32_e32 v123, v123, v15
	v_exp_f32_e32 v123, v123
	v_add_f32_e32 v238, v122, v238
	v_add_f32_e32 v124, v124, v15
	v_exp_f32_e32 v124, v124
	v_add_f32_e32 v238, v123, v238
	s_waitcnt lgkmcnt(2)
	v_mfma_f32_32x32x16_bf16 v[32:47], v[240:243], v[160:163], v[32:47]
	v_add_f32_e32 v125, v125, v15
	v_exp_f32_e32 v125, v125
	v_add_f32_e32 v238, v124, v238
	s_waitcnt lgkmcnt(0)
	v_mfma_f32_32x32x16_bf16 v[16:31], v[244:247], v[160:163], v[16:31]
	v_add_f32_e32 v126, v126, v15
	v_exp_f32_e32 v126, v126
	v_add_f32_e32 v238, v125, v238
	v_add_f32_e32 v127, v127, v15
	v_exp_f32_e32 v127, v127
	v_add_f32_e32 v238, v126, v238
	v_cvt_pk_bf16_f32 v160, v120, v121
	v_cvt_pk_bf16_f32 v161, v122, v123
	v_cvt_pk_bf16_f32 v162, v124, v125
	v_cvt_pk_bf16_f32 v163, v126, v127
	v_add_f32_e32 v238, v127, v238
	v_fmac_f32_e32 v238, v232, v0
	s_mov_b32 s27, s30
	v_mov_b32_e32 v232, v238
	s_and_b64 vcc, exec, s[38:39]
	s_cbranch_vccz .LBB0_477
	s_branch .LBB0_480
